# v14 plus software-pipelined bpermute/store in P3/P5/P6 epilogues
# baseline (speedup 1.0000x reference)
.LBB0_524:
	s_lshl_b32 s9, s51, 8
	s_add_i32 s23, s9, 0xffffe000
	s_cmp_eq_u32 s50, 0
	s_cselect_b32 s9, s9, s23
	s_mov_b32 s23, 0x21c00000
	s_cselect_b32 s23, s23, 0x33c00000
	s_add_u32 s50, s94, s23
	v_lshl_or_b32 v146, s22, 8, v143
	v_add_u32_e32 v148, s9, v1
	s_addc_u32 s51, s95, 0
	v_ashrrev_i32_e32 v147, 31, v146
	v_ashrrev_i32_e32 v149, 31, v148
	v_lshl_add_u64 v[146:147], v[146:147], 1, s[50:51]
	v_lshlrev_b64 v[150:151], 12, v[148:149]
	v_lshl_add_u64 v[150:151], v[146:147], 0, v[150:151]
	s_mov_b32 s9, 0x80000
	s_mov_b64 s[50:51], 0x80000
	v_cvt_pk_bf16_f32 v64, v64, v65
	v_cvt_pk_bf16_f32 v65, v66, v67
	v_cvt_pk_bf16_f32 v66, v60, v61
	v_add_co_u32_e32 v60, vcc, s9, v150
	v_cvt_pk_bf16_f32 v72, v72, v73
	v_cvt_pk_bf16_f32 v73, v74, v75
	v_cvt_pk_bf16_f32 v74, v68, v69
	v_lshl_add_u64 v[68:69], v[150:151], 0, s[50:51]
	v_addc_co_u32_e32 v61, vcc, 0, v151, vcc
	v_cvt_pk_bf16_f32 v48, v48, v49
	v_cvt_pk_bf16_f32 v49, v50, v51
	v_cvt_pk_bf16_f32 v50, v44, v45
	v_cvt_pk_bf16_f32 v51, v46, v47
	s_mov_b32 s9, 0x90000
	ds_bpermute_b32 v222, v231, v48
	ds_bpermute_b32 v223, v231, v49
	ds_bpermute_b32 v224, v231, v50
	ds_bpermute_b32 v225, v231, v51
	s_mov_b64 s[50:51], 0x90000
	v_cvt_pk_bf16_f32 v112, v112, v113
	v_add_co_u32_e32 v50, vcc, s9, v150
	v_cvt_pk_bf16_f32 v113, v114, v115
	v_cvt_pk_bf16_f32 v114, v108, v109
	v_or_b32_e32 v108, 16, v148
	v_lshl_add_u64 v[48:49], v[150:151], 0, s[50:51]
	v_addc_co_u32_e32 v51, vcc, 0, v151, vcc
	v_cvt_pk_bf16_f32 v32, v32, v33
	v_cvt_pk_bf16_f32 v33, v34, v35
	v_cvt_pk_bf16_f32 v34, v28, v29
	v_cvt_pk_bf16_f32 v35, v30, v31
	s_mov_b32 s9, 0xa0000
	v_ashrrev_i32_e32 v109, 31, v108
	v_cvt_pk_bf16_f32 v96, v96, v97
	v_cvt_pk_bf16_f32 v97, v98, v99
	v_cvt_pk_bf16_f32 v98, v92, v93
	v_or_b32_e32 v92, 32, v148
	s_waitcnt lgkmcnt(0)
	global_store_dwordx4 v[68:69], v[222:225], off offset:256
	ds_bpermute_b32 v226, v231, v32
	ds_bpermute_b32 v227, v231, v33
	ds_bpermute_b32 v228, v231, v34
	ds_bpermute_b32 v229, v231, v35
	s_mov_b64 s[50:51], 0xa0000
	v_cvt_pk_bf16_f32 v115, v110, v111
	v_add_co_u32_e32 v34, vcc, s9, v150
	v_lshlrev_b64 v[108:109], 12, v[108:109]
	v_ashrrev_i32_e32 v93, 31, v92
	v_cvt_pk_bf16_f32 v80, v80, v81
	v_cvt_pk_bf16_f32 v81, v82, v83
	v_cvt_pk_bf16_f32 v82, v76, v77
	v_or_b32_e32 v76, 48, v148
	v_lshl_add_u64 v[32:33], v[150:151], 0, s[50:51]
	v_addc_co_u32_e32 v35, vcc, 0, v151, vcc
	v_cvt_pk_bf16_f32 v16, v16, v17
	v_cvt_pk_bf16_f32 v17, v18, v19
	v_cvt_pk_bf16_f32 v18, v12, v13
	v_cvt_pk_bf16_f32 v19, v14, v15
	s_mov_b32 s9, 0xb0000
	s_waitcnt lgkmcnt(0)
	global_store_dwordx4 v[48:49], v[226:229], off offset:256
	ds_bpermute_b32 v222, v231, v112
	ds_bpermute_b32 v223, v231, v113
	ds_bpermute_b32 v224, v231, v114
	ds_bpermute_b32 v225, v231, v115
	v_cvt_pk_bf16_f32 v99, v94, v95
	v_lshlrev_b64 v[92:93], 12, v[92:93]
	v_lshl_add_u64 v[112:113], v[146:147], 0, v[108:109]
	v_ashrrev_i32_e32 v77, 31, v76
	s_waitcnt lgkmcnt(0)
	global_store_dwordx4 v[150:151], v[222:225], off offset:256
	ds_bpermute_b32 v226, v231, v16
	ds_bpermute_b32 v227, v231, v17
	ds_bpermute_b32 v228, v231, v18
	ds_bpermute_b32 v229, v231, v19
	s_waitcnt lgkmcnt(0)
	global_store_dwordx4 v[32:33], v[226:229], off offset:256
	ds_bpermute_b32 v222, v231, v96
	ds_bpermute_b32 v223, v231, v97
	ds_bpermute_b32 v224, v231, v98
	ds_bpermute_b32 v225, v231, v99
	v_cvt_pk_bf16_f32 v83, v78, v79
	v_add_co_u32_e32 v18, vcc, s9, v150
	v_lshl_add_u64 v[96:97], v[146:147], 0, v[92:93]
	v_lshlrev_b64 v[76:77], 12, v[76:77]
	s_mov_b64 s[50:51], 0xb0000
	v_addc_co_u32_e32 v19, vcc, 0, v151, vcc
	v_cvt_pk_bf16_f32 v128, v128, v129
	v_cvt_pk_bf16_f32 v129, v130, v131
	v_cvt_pk_bf16_f32 v130, v124, v125
	v_cvt_pk_bf16_f32 v131, v126, v127
	v_cvt_pk_bf16_f32 v108, v120, v121
	v_cvt_pk_bf16_f32 v109, v122, v123
	v_cvt_pk_bf16_f32 v110, v116, v117
	v_cvt_pk_bf16_f32 v111, v118, v119
	v_cvt_pk_bf16_f32 v92, v104, v105
	v_cvt_pk_bf16_f32 v93, v106, v107
	v_cvt_pk_bf16_f32 v94, v100, v101
	v_cvt_pk_bf16_f32 v95, v102, v103
	s_waitcnt lgkmcnt(0)
	global_store_dwordx4 v[112:113], v[222:225], off offset:256
	ds_bpermute_b32 v226, v231, v80
	ds_bpermute_b32 v227, v231, v81
	ds_bpermute_b32 v228, v231, v82
	ds_bpermute_b32 v229, v231, v83
	v_cvt_pk_bf16_f32 v78, v84, v85
	v_cvt_pk_bf16_f32 v79, v86, v87
	v_lshl_add_u64 v[80:81], v[146:147], 0, v[76:77]
	v_cvt_pk_bf16_f32 v76, v88, v89
	v_cvt_pk_bf16_f32 v77, v90, v91
	v_cvt_pk_bf16_f32 v75, v70, v71
	v_cvt_pk_bf16_f32 v67, v62, v63
	v_cvt_pk_bf16_f32 v44, v56, v57
	v_cvt_pk_bf16_f32 v45, v58, v59
	v_cvt_pk_bf16_f32 v46, v52, v53
	v_cvt_pk_bf16_f32 v47, v54, v55
	v_cvt_pk_bf16_f32 v28, v40, v41
	v_cvt_pk_bf16_f32 v29, v42, v43
	v_cvt_pk_bf16_f32 v30, v36, v37
	v_cvt_pk_bf16_f32 v31, v38, v39
	v_lshl_add_u64 v[16:17], v[150:151], 0, s[50:51]
	v_cvt_pk_bf16_f32 v12, v24, v25
	v_cvt_pk_bf16_f32 v13, v26, v27
	v_cvt_pk_bf16_f32 v14, v20, v21
	v_cvt_pk_bf16_f32 v15, v22, v23
	v_cvt_pk_bf16_f32 v8, v8, v9
	v_cvt_pk_bf16_f32 v9, v10, v11
	v_cvt_pk_bf16_f32 v10, v4, v5
	v_cvt_pk_bf16_f32 v11, v6, v7
	s_and_b64 vcc, exec, s[0:1]
	s_mov_b64 s[0:1], -1
	s_waitcnt lgkmcnt(0)
	global_store_dwordx4 v[96:97], v[226:229], off offset:256
	ds_bpermute_b32 v222, v231, v128
	ds_bpermute_b32 v223, v231, v129
	ds_bpermute_b32 v224, v231, v130
	ds_bpermute_b32 v225, v231, v131
	s_waitcnt lgkmcnt(0)
	global_store_dwordx4 v[150:151], v[222:225], off
	ds_bpermute_b32 v226, v231, v108
	ds_bpermute_b32 v227, v231, v109
	ds_bpermute_b32 v228, v231, v110
	ds_bpermute_b32 v229, v231, v111
	s_waitcnt lgkmcnt(0)
	global_store_dwordx4 v[112:113], v[226:229], off
	ds_bpermute_b32 v222, v231, v92
	ds_bpermute_b32 v223, v231, v93
	ds_bpermute_b32 v224, v231, v94
	ds_bpermute_b32 v225, v231, v95
	s_waitcnt lgkmcnt(0)
	global_store_dwordx4 v[96:97], v[222:225], off
	ds_bpermute_b32 v226, v231, v76
	ds_bpermute_b32 v227, v231, v77
	ds_bpermute_b32 v228, v231, v78
	ds_bpermute_b32 v229, v231, v79
	s_waitcnt lgkmcnt(0)
	global_store_dwordx4 v[80:81], v[226:229], off
	ds_bpermute_b32 v222, v231, v72
	ds_bpermute_b32 v223, v231, v73
	ds_bpermute_b32 v224, v231, v74
	ds_bpermute_b32 v225, v231, v75
	s_waitcnt lgkmcnt(0)
	global_store_dwordx4 v[80:81], v[222:225], off offset:256
	ds_bpermute_b32 v226, v231, v64
	ds_bpermute_b32 v227, v231, v65
	ds_bpermute_b32 v228, v231, v66
	ds_bpermute_b32 v229, v231, v67
	s_waitcnt lgkmcnt(0)
	global_store_dwordx4 v[60:61], v[226:229], off
	ds_bpermute_b32 v222, v231, v44
	ds_bpermute_b32 v223, v231, v45
	ds_bpermute_b32 v224, v231, v46
	ds_bpermute_b32 v225, v231, v47
	s_waitcnt lgkmcnt(0)
	global_store_dwordx4 v[50:51], v[222:225], off
	ds_bpermute_b32 v226, v231, v28
	ds_bpermute_b32 v227, v231, v29
	ds_bpermute_b32 v228, v231, v30
	ds_bpermute_b32 v229, v231, v31
	s_waitcnt lgkmcnt(0)
	global_store_dwordx4 v[34:35], v[226:229], off
	ds_bpermute_b32 v222, v231, v12
	ds_bpermute_b32 v223, v231, v13
	ds_bpermute_b32 v224, v231, v14
	ds_bpermute_b32 v225, v231, v15
	s_waitcnt lgkmcnt(0)
	global_store_dwordx4 v[18:19], v[222:225], off
	ds_bpermute_b32 v226, v231, v8
	ds_bpermute_b32 v227, v231, v9
	ds_bpermute_b32 v228, v231, v10
	ds_bpermute_b32 v229, v231, v11
	s_waitcnt lgkmcnt(0)
	global_store_dwordx4 v[16:17], v[226:229], off offset:256
	s_cbranch_vccnz .LBB0_515
	s_andn2_b64 vcc, exec, s[36:37]
	s_cbranch_vccnz .LBB0_514
	s_barrier
	s_branch .LBB0_514

.LBB0_697:
	v_max_f32_e32 v124, v124, v124
	v_max_f32_e32 v125, v125, v125
	v_max_f32_e32 v124, 0, v124
	v_max_f32_e32 v125, 0, v125
	v_pk_mul_f32 v[152:153], v[124:125], v[124:125]
	v_max_f32_e32 v125, v126, v126
	v_lshl_or_b32 v142, s12, 8, v145
	v_lshl_add_u32 v148, s13, 8, v1
	v_max_f32_e32 v128, v128, v128
	v_max_f32_e32 v129, v129, v129
	v_max_f32_e32 v124, v130, v130
	v_max_f32_e32 v126, 0, v125
	v_max_f32_e32 v125, v131, v131
	v_max_f32_e32 v127, v127, v127
	v_ashrrev_i32_e32 v143, 31, v142
	v_ashrrev_i32_e32 v149, 31, v148
	v_max_f32_e32 v128, 0, v128
	v_max_f32_e32 v129, 0, v129
	v_max_f32_e32 v124, 0, v124
	v_max_f32_e32 v125, 0, v125
	v_max_f32_e32 v127, 0, v127
	v_lshl_add_u64 v[150:151], v[142:143], 1, s[38:39]
	v_lshlrev_b64 v[142:143], 14, v[148:149]
	v_pk_mul_f32 v[128:129], v[128:129], v[128:129]
	v_pk_mul_f32 v[130:131], v[124:125], v[124:125]
	v_pk_mul_f32 v[154:155], v[126:127], v[126:127]
	v_max_f32_e32 v116, v116, v116
	v_max_f32_e32 v117, v117, v117
	v_lshl_add_u64 v[142:143], v[150:151], 0, v[142:143]
	v_cvt_pk_bf16_f32 v124, v128, v129
	v_cvt_pk_bf16_f32 v125, v130, v131
	v_cvt_pk_bf16_f32 v126, v152, v153
	v_cvt_pk_bf16_f32 v127, v154, v155
	v_max_f32_e32 v116, 0, v116
	v_max_f32_e32 v117, 0, v117
	ds_bpermute_b32 v222, v231, v124
	ds_bpermute_b32 v223, v231, v125
	ds_bpermute_b32 v224, v231, v126
	ds_bpermute_b32 v225, v231, v127
	v_max_f32_e32 v120, v120, v120
	v_max_f32_e32 v121, v121, v121
	v_pk_mul_f32 v[124:125], v[116:117], v[116:117]
	v_max_f32_e32 v117, v118, v118
	v_max_f32_e32 v116, v122, v122
	v_max_f32_e32 v118, 0, v117
	v_max_f32_e32 v117, v123, v123
	v_max_f32_e32 v119, v119, v119
	v_max_f32_e32 v120, 0, v120
	v_max_f32_e32 v121, 0, v121
	v_max_f32_e32 v116, 0, v116
	v_max_f32_e32 v117, 0, v117
	v_max_f32_e32 v119, 0, v119
	v_pk_mul_f32 v[120:121], v[120:121], v[120:121]
	v_pk_mul_f32 v[122:123], v[116:117], v[116:117]
	v_pk_mul_f32 v[126:127], v[118:119], v[118:119]
	v_max_f32_e32 v108, v108, v108
	v_max_f32_e32 v109, v109, v109
	v_cvt_pk_bf16_f32 v116, v120, v121
	v_cvt_pk_bf16_f32 v117, v122, v123
	v_cvt_pk_bf16_f32 v118, v124, v125
	v_cvt_pk_bf16_f32 v119, v126, v127
	v_max_f32_e32 v108, 0, v108
	v_max_f32_e32 v109, 0, v109
	s_waitcnt lgkmcnt(0)
	global_store_dwordx4 v[142:143], v[222:225], off
	ds_bpermute_b32 v226, v231, v116
	ds_bpermute_b32 v227, v231, v117
	ds_bpermute_b32 v228, v231, v118
	ds_bpermute_b32 v229, v231, v119
	v_max_f32_e32 v112, v112, v112
	v_max_f32_e32 v113, v113, v113
	v_pk_mul_f32 v[118:119], v[108:109], v[108:109]
	v_max_f32_e32 v109, v110, v110
	v_or_b32_e32 v116, 16, v148
	v_max_f32_e32 v108, v114, v114
	v_max_f32_e32 v110, 0, v109
	v_max_f32_e32 v109, v115, v115
	v_max_f32_e32 v111, v111, v111
	v_ashrrev_i32_e32 v117, 31, v116
	v_max_f32_e32 v112, 0, v112
	v_max_f32_e32 v113, 0, v113
	v_max_f32_e32 v108, 0, v108
	v_max_f32_e32 v109, 0, v109
	v_max_f32_e32 v111, 0, v111
	v_lshlrev_b64 v[116:117], 14, v[116:117]
	v_pk_mul_f32 v[112:113], v[112:113], v[112:113]
	v_pk_mul_f32 v[114:115], v[108:109], v[108:109]
	v_pk_mul_f32 v[120:121], v[110:111], v[110:111]
	v_max_f32_e32 v100, v100, v100
	v_max_f32_e32 v101, v101, v101
	v_lshl_add_u64 v[116:117], v[150:151], 0, v[116:117]
	v_cvt_pk_bf16_f32 v108, v112, v113
	v_cvt_pk_bf16_f32 v109, v114, v115
	v_cvt_pk_bf16_f32 v110, v118, v119
	v_cvt_pk_bf16_f32 v111, v120, v121
	v_max_f32_e32 v100, 0, v100
	v_max_f32_e32 v101, 0, v101
	s_waitcnt lgkmcnt(0)
	global_store_dwordx4 v[142:143], v[226:229], off offset:256
	ds_bpermute_b32 v222, v231, v108
	ds_bpermute_b32 v223, v231, v109
	ds_bpermute_b32 v224, v231, v110
	ds_bpermute_b32 v225, v231, v111
	v_max_f32_e32 v104, v104, v104
	v_max_f32_e32 v105, v105, v105
	v_pk_mul_f32 v[108:109], v[100:101], v[100:101]
	v_max_f32_e32 v101, v102, v102
	v_max_f32_e32 v100, v106, v106
	v_max_f32_e32 v102, 0, v101
	v_max_f32_e32 v101, v107, v107
	v_max_f32_e32 v103, v103, v103
	v_max_f32_e32 v104, 0, v104
	v_max_f32_e32 v105, 0, v105
	v_max_f32_e32 v100, 0, v100
	v_max_f32_e32 v101, 0, v101
	v_max_f32_e32 v103, 0, v103
	v_pk_mul_f32 v[104:105], v[104:105], v[104:105]
	v_pk_mul_f32 v[106:107], v[100:101], v[100:101]
	v_pk_mul_f32 v[110:111], v[102:103], v[102:103]
	v_max_f32_e32 v92, v92, v92
	v_max_f32_e32 v93, v93, v93
	v_cvt_pk_bf16_f32 v100, v104, v105
	v_cvt_pk_bf16_f32 v101, v106, v107
	v_cvt_pk_bf16_f32 v102, v108, v109
	v_cvt_pk_bf16_f32 v103, v110, v111
	v_max_f32_e32 v92, 0, v92
	v_max_f32_e32 v93, 0, v93
	s_waitcnt lgkmcnt(0)
	global_store_dwordx4 v[116:117], v[222:225], off
	ds_bpermute_b32 v226, v231, v100
	ds_bpermute_b32 v227, v231, v101
	ds_bpermute_b32 v228, v231, v102
	ds_bpermute_b32 v229, v231, v103
	v_max_f32_e32 v96, v96, v96
	v_max_f32_e32 v97, v97, v97
	v_pk_mul_f32 v[102:103], v[92:93], v[92:93]
	v_max_f32_e32 v93, v94, v94
	v_or_b32_e32 v100, 32, v148
	v_max_f32_e32 v92, v98, v98
	v_max_f32_e32 v94, 0, v93
	v_max_f32_e32 v93, v99, v99
	v_max_f32_e32 v95, v95, v95
	v_ashrrev_i32_e32 v101, 31, v100
	v_max_f32_e32 v96, 0, v96
	v_max_f32_e32 v97, 0, v97
	v_max_f32_e32 v92, 0, v92
	v_max_f32_e32 v93, 0, v93
	v_max_f32_e32 v95, 0, v95
	v_lshlrev_b64 v[100:101], 14, v[100:101]
	v_pk_mul_f32 v[96:97], v[96:97], v[96:97]
	v_pk_mul_f32 v[98:99], v[92:93], v[92:93]
	v_pk_mul_f32 v[104:105], v[94:95], v[94:95]
	v_max_f32_e32 v84, v84, v84
	v_max_f32_e32 v85, v85, v85
	v_lshl_add_u64 v[100:101], v[150:151], 0, v[100:101]
	v_cvt_pk_bf16_f32 v92, v96, v97
	v_cvt_pk_bf16_f32 v93, v98, v99
	v_cvt_pk_bf16_f32 v94, v102, v103
	v_cvt_pk_bf16_f32 v95, v104, v105
	v_max_f32_e32 v84, 0, v84
	v_max_f32_e32 v85, 0, v85
	s_waitcnt lgkmcnt(0)
	global_store_dwordx4 v[116:117], v[226:229], off offset:256
	ds_bpermute_b32 v222, v231, v92
	ds_bpermute_b32 v223, v231, v93
	ds_bpermute_b32 v224, v231, v94
	ds_bpermute_b32 v225, v231, v95
	v_max_f32_e32 v88, v88, v88
	v_max_f32_e32 v89, v89, v89
	v_pk_mul_f32 v[92:93], v[84:85], v[84:85]
	v_max_f32_e32 v85, v86, v86
	v_max_f32_e32 v84, v90, v90
	v_max_f32_e32 v86, 0, v85
	v_max_f32_e32 v85, v91, v91
	v_max_f32_e32 v87, v87, v87
	v_max_f32_e32 v88, 0, v88
	v_max_f32_e32 v89, 0, v89
	v_max_f32_e32 v84, 0, v84
	v_max_f32_e32 v85, 0, v85
	v_max_f32_e32 v87, 0, v87
	v_pk_mul_f32 v[88:89], v[88:89], v[88:89]
	v_pk_mul_f32 v[90:91], v[84:85], v[84:85]
	v_pk_mul_f32 v[94:95], v[86:87], v[86:87]
	v_max_f32_e32 v76, v76, v76
	v_max_f32_e32 v77, v77, v77
	v_cvt_pk_bf16_f32 v84, v88, v89
	v_cvt_pk_bf16_f32 v85, v90, v91
	v_cvt_pk_bf16_f32 v86, v92, v93
	v_cvt_pk_bf16_f32 v87, v94, v95
	v_max_f32_e32 v76, 0, v76
	v_max_f32_e32 v77, 0, v77
	s_waitcnt lgkmcnt(0)
	global_store_dwordx4 v[100:101], v[222:225], off
	ds_bpermute_b32 v226, v231, v84
	ds_bpermute_b32 v227, v231, v85
	ds_bpermute_b32 v228, v231, v86
	ds_bpermute_b32 v229, v231, v87
	v_max_f32_e32 v80, v80, v80
	v_max_f32_e32 v81, v81, v81
	v_pk_mul_f32 v[86:87], v[76:77], v[76:77]
	v_max_f32_e32 v77, v78, v78
	v_or_b32_e32 v84, 48, v148
	v_max_f32_e32 v76, v82, v82
	v_max_f32_e32 v78, 0, v77
	v_max_f32_e32 v77, v83, v83
	v_max_f32_e32 v79, v79, v79
	v_ashrrev_i32_e32 v85, 31, v84
	v_max_f32_e32 v80, 0, v80
	v_max_f32_e32 v81, 0, v81
	v_max_f32_e32 v76, 0, v76
	v_max_f32_e32 v77, 0, v77
	v_max_f32_e32 v79, 0, v79
	v_lshlrev_b64 v[84:85], 14, v[84:85]
	v_pk_mul_f32 v[80:81], v[80:81], v[80:81]
	v_pk_mul_f32 v[82:83], v[76:77], v[76:77]
	v_pk_mul_f32 v[88:89], v[78:79], v[78:79]
	v_max_f32_e32 v68, v68, v68
	v_max_f32_e32 v69, v69, v69
	v_lshl_add_u64 v[84:85], v[150:151], 0, v[84:85]
	v_cvt_pk_bf16_f32 v76, v80, v81
	v_cvt_pk_bf16_f32 v77, v82, v83
	v_cvt_pk_bf16_f32 v78, v86, v87
	v_cvt_pk_bf16_f32 v79, v88, v89
	v_max_f32_e32 v68, 0, v68
	v_max_f32_e32 v69, 0, v69
	s_waitcnt lgkmcnt(0)
	global_store_dwordx4 v[100:101], v[226:229], off offset:256
	ds_bpermute_b32 v222, v231, v76
	ds_bpermute_b32 v223, v231, v77
	ds_bpermute_b32 v224, v231, v78
	ds_bpermute_b32 v225, v231, v79
	v_max_f32_e32 v72, v72, v72
	v_max_f32_e32 v73, v73, v73
	v_pk_mul_f32 v[76:77], v[68:69], v[68:69]
	v_max_f32_e32 v69, v70, v70
	v_max_f32_e32 v68, v74, v74
	v_max_f32_e32 v70, 0, v69
	v_max_f32_e32 v69, v75, v75
	v_max_f32_e32 v71, v71, v71
	v_max_f32_e32 v72, 0, v72
	v_max_f32_e32 v73, 0, v73
	v_max_f32_e32 v68, 0, v68
	v_max_f32_e32 v69, 0, v69
	v_max_f32_e32 v71, 0, v71
	v_pk_mul_f32 v[72:73], v[72:73], v[72:73]
	v_pk_mul_f32 v[74:75], v[68:69], v[68:69]
	v_pk_mul_f32 v[78:79], v[70:71], v[70:71]
	v_max_f32_e32 v60, v60, v60
	v_max_f32_e32 v61, v61, v61
	v_cvt_pk_bf16_f32 v68, v72, v73
	v_cvt_pk_bf16_f32 v69, v74, v75
	v_cvt_pk_bf16_f32 v70, v76, v77
	v_cvt_pk_bf16_f32 v71, v78, v79
	v_max_f32_e32 v60, 0, v60
	v_max_f32_e32 v61, 0, v61
	s_waitcnt lgkmcnt(0)
	global_store_dwordx4 v[84:85], v[222:225], off
	ds_bpermute_b32 v226, v231, v68
	ds_bpermute_b32 v227, v231, v69
	ds_bpermute_b32 v228, v231, v70
	ds_bpermute_b32 v229, v231, v71
	v_max_f32_e32 v64, v64, v64
	v_max_f32_e32 v65, v65, v65
	v_pk_mul_f32 v[70:71], v[60:61], v[60:61]
	v_max_f32_e32 v61, v62, v62
	s_mov_b64 s[12:13], 0x200000
	v_max_f32_e32 v64, 0, v64
	v_max_f32_e32 v65, 0, v65
	v_max_f32_e32 v60, v66, v66
	v_max_f32_e32 v62, 0, v61
	v_max_f32_e32 v61, v67, v67
	v_max_f32_e32 v63, v63, v63
	v_lshl_add_u64 v[68:69], v[142:143], 0, s[12:13]
	v_pk_mul_f32 v[64:65], v[64:65], v[64:65]
	v_max_f32_e32 v60, 0, v60
	v_max_f32_e32 v61, 0, v61
	v_max_f32_e32 v63, 0, v63
	s_mov_b32 s12, 0x200000
	v_pk_mul_f32 v[66:67], v[60:61], v[60:61]
	v_pk_mul_f32 v[72:73], v[62:63], v[62:63]
	v_cvt_pk_bf16_f32 v60, v64, v65
	v_add_co_u32_e32 v64, vcc, s12, v142
	v_max_f32_e32 v52, v52, v52
	v_max_f32_e32 v53, v53, v53
	v_cvt_pk_bf16_f32 v61, v66, v67
	v_cvt_pk_bf16_f32 v62, v70, v71
	v_cvt_pk_bf16_f32 v63, v72, v73
	v_addc_co_u32_e32 v65, vcc, 0, v143, vcc
	v_max_f32_e32 v52, 0, v52
	v_max_f32_e32 v53, 0, v53
	s_waitcnt lgkmcnt(0)
	global_store_dwordx4 v[84:85], v[226:229], off offset:256
	ds_bpermute_b32 v222, v231, v60
	ds_bpermute_b32 v223, v231, v61
	ds_bpermute_b32 v224, v231, v62
	ds_bpermute_b32 v225, v231, v63
	v_max_f32_e32 v56, v56, v56
	v_max_f32_e32 v57, v57, v57
	v_pk_mul_f32 v[60:61], v[52:53], v[52:53]
	v_max_f32_e32 v53, v54, v54
	v_max_f32_e32 v52, v58, v58
	v_max_f32_e32 v54, 0, v53
	v_max_f32_e32 v53, v59, v59
	v_max_f32_e32 v55, v55, v55
	v_max_f32_e32 v56, 0, v56
	v_max_f32_e32 v57, 0, v57
	v_max_f32_e32 v52, 0, v52
	v_max_f32_e32 v53, 0, v53
	v_max_f32_e32 v55, 0, v55
	v_pk_mul_f32 v[56:57], v[56:57], v[56:57]
	v_pk_mul_f32 v[58:59], v[52:53], v[52:53]
	v_pk_mul_f32 v[62:63], v[54:55], v[54:55]
	v_max_f32_e32 v44, v44, v44
	v_max_f32_e32 v45, v45, v45
	v_cvt_pk_bf16_f32 v52, v56, v57
	v_cvt_pk_bf16_f32 v53, v58, v59
	v_cvt_pk_bf16_f32 v54, v60, v61
	v_cvt_pk_bf16_f32 v55, v62, v63
	v_max_f32_e32 v44, 0, v44
	v_max_f32_e32 v45, 0, v45
	s_waitcnt lgkmcnt(0)
	global_store_dwordx4 v[64:65], v[222:225], off
	ds_bpermute_b32 v226, v231, v52
	ds_bpermute_b32 v227, v231, v53
	ds_bpermute_b32 v228, v231, v54
	ds_bpermute_b32 v229, v231, v55
	v_max_f32_e32 v48, v48, v48
	v_max_f32_e32 v49, v49, v49
	v_pk_mul_f32 v[54:55], v[44:45], v[44:45]
	v_max_f32_e32 v45, v46, v46
	s_mov_b64 s[12:13], 0x240000
	v_max_f32_e32 v48, 0, v48
	v_max_f32_e32 v49, 0, v49
	v_max_f32_e32 v44, v50, v50
	v_max_f32_e32 v46, 0, v45
	v_max_f32_e32 v45, v51, v51
	v_max_f32_e32 v47, v47, v47
	v_lshl_add_u64 v[52:53], v[142:143], 0, s[12:13]
	v_pk_mul_f32 v[48:49], v[48:49], v[48:49]
	v_max_f32_e32 v44, 0, v44
	v_max_f32_e32 v45, 0, v45
	v_max_f32_e32 v47, 0, v47
	s_mov_b32 s12, 0x240000
	v_pk_mul_f32 v[50:51], v[44:45], v[44:45]
	v_pk_mul_f32 v[56:57], v[46:47], v[46:47]
	v_cvt_pk_bf16_f32 v44, v48, v49
	v_add_co_u32_e32 v48, vcc, s12, v142
	v_max_f32_e32 v36, v36, v36
	v_max_f32_e32 v37, v37, v37
	v_cvt_pk_bf16_f32 v45, v50, v51
	v_cvt_pk_bf16_f32 v46, v54, v55
	v_cvt_pk_bf16_f32 v47, v56, v57
	v_addc_co_u32_e32 v49, vcc, 0, v143, vcc
	v_max_f32_e32 v36, 0, v36
	v_max_f32_e32 v37, 0, v37
	s_waitcnt lgkmcnt(0)
	global_store_dwordx4 v[68:69], v[226:229], off offset:256
	ds_bpermute_b32 v222, v231, v44
	ds_bpermute_b32 v223, v231, v45
	ds_bpermute_b32 v224, v231, v46
	ds_bpermute_b32 v225, v231, v47
	v_max_f32_e32 v40, v40, v40
	v_max_f32_e32 v41, v41, v41
	v_pk_mul_f32 v[44:45], v[36:37], v[36:37]
	v_max_f32_e32 v37, v38, v38
	v_max_f32_e32 v36, v42, v42
	v_max_f32_e32 v38, 0, v37
	v_max_f32_e32 v37, v43, v43
	v_max_f32_e32 v39, v39, v39
	v_max_f32_e32 v40, 0, v40
	v_max_f32_e32 v41, 0, v41
	v_max_f32_e32 v36, 0, v36
	v_max_f32_e32 v37, 0, v37
	v_max_f32_e32 v39, 0, v39
	v_pk_mul_f32 v[40:41], v[40:41], v[40:41]
	v_pk_mul_f32 v[42:43], v[36:37], v[36:37]
	v_pk_mul_f32 v[46:47], v[38:39], v[38:39]
	v_max_f32_e32 v28, v28, v28
	v_max_f32_e32 v29, v29, v29
	v_cvt_pk_bf16_f32 v36, v40, v41
	v_cvt_pk_bf16_f32 v37, v42, v43
	v_cvt_pk_bf16_f32 v38, v44, v45
	v_cvt_pk_bf16_f32 v39, v46, v47
	v_max_f32_e32 v28, 0, v28
	v_max_f32_e32 v29, 0, v29
	s_waitcnt lgkmcnt(0)
	global_store_dwordx4 v[48:49], v[222:225], off
	ds_bpermute_b32 v226, v231, v36
	ds_bpermute_b32 v227, v231, v37
	ds_bpermute_b32 v228, v231, v38
	ds_bpermute_b32 v229, v231, v39
	v_max_f32_e32 v32, v32, v32
	v_max_f32_e32 v33, v33, v33
	v_pk_mul_f32 v[38:39], v[28:29], v[28:29]
	v_max_f32_e32 v29, v30, v30
	s_mov_b64 s[12:13], 0x280000
	v_max_f32_e32 v32, 0, v32
	v_max_f32_e32 v33, 0, v33
	v_max_f32_e32 v28, v34, v34
	v_max_f32_e32 v30, 0, v29
	v_max_f32_e32 v29, v35, v35
	v_max_f32_e32 v31, v31, v31
	v_lshl_add_u64 v[36:37], v[142:143], 0, s[12:13]
	v_pk_mul_f32 v[32:33], v[32:33], v[32:33]
	v_max_f32_e32 v28, 0, v28
	v_max_f32_e32 v29, 0, v29
	v_max_f32_e32 v31, 0, v31
	s_mov_b32 s12, 0x280000
	v_pk_mul_f32 v[34:35], v[28:29], v[28:29]
	v_pk_mul_f32 v[40:41], v[30:31], v[30:31]
	v_cvt_pk_bf16_f32 v28, v32, v33
	v_add_co_u32_e32 v32, vcc, s12, v142
	v_max_f32_e32 v20, v20, v20
	v_max_f32_e32 v21, v21, v21
	v_cvt_pk_bf16_f32 v29, v34, v35
	v_cvt_pk_bf16_f32 v30, v38, v39
	v_cvt_pk_bf16_f32 v31, v40, v41
	v_addc_co_u32_e32 v33, vcc, 0, v143, vcc
	v_max_f32_e32 v20, 0, v20
	v_max_f32_e32 v21, 0, v21
	s_waitcnt lgkmcnt(0)
	global_store_dwordx4 v[52:53], v[226:229], off offset:256
	ds_bpermute_b32 v222, v231, v28
	ds_bpermute_b32 v223, v231, v29
	ds_bpermute_b32 v224, v231, v30
	ds_bpermute_b32 v225, v231, v31
	v_max_f32_e32 v24, v24, v24
	v_max_f32_e32 v25, v25, v25
	v_pk_mul_f32 v[28:29], v[20:21], v[20:21]
	v_max_f32_e32 v21, v22, v22
	v_max_f32_e32 v20, v26, v26
	v_max_f32_e32 v22, 0, v21
	v_max_f32_e32 v21, v27, v27
	v_max_f32_e32 v23, v23, v23
	v_max_f32_e32 v24, 0, v24
	v_max_f32_e32 v25, 0, v25
	v_max_f32_e32 v20, 0, v20
	v_max_f32_e32 v21, 0, v21
	v_max_f32_e32 v23, 0, v23
	v_pk_mul_f32 v[24:25], v[24:25], v[24:25]
	v_pk_mul_f32 v[26:27], v[20:21], v[20:21]
	v_pk_mul_f32 v[30:31], v[22:23], v[22:23]
	v_max_f32_e32 v12, v12, v12
	v_max_f32_e32 v13, v13, v13
	v_cvt_pk_bf16_f32 v20, v24, v25
	v_cvt_pk_bf16_f32 v21, v26, v27
	v_cvt_pk_bf16_f32 v22, v28, v29
	v_cvt_pk_bf16_f32 v23, v30, v31
	v_max_f32_e32 v12, 0, v12
	v_max_f32_e32 v13, 0, v13
	s_waitcnt lgkmcnt(0)
	global_store_dwordx4 v[32:33], v[222:225], off
	ds_bpermute_b32 v226, v231, v20
	ds_bpermute_b32 v227, v231, v21
	ds_bpermute_b32 v228, v231, v22
	ds_bpermute_b32 v229, v231, v23
	v_max_f32_e32 v16, v16, v16
	v_max_f32_e32 v17, v17, v17
	v_pk_mul_f32 v[22:23], v[12:13], v[12:13]
	v_max_f32_e32 v13, v14, v14
	s_mov_b64 s[12:13], 0x2c0000
	v_max_f32_e32 v16, 0, v16
	v_max_f32_e32 v17, 0, v17
	v_max_f32_e32 v12, v18, v18
	v_max_f32_e32 v14, 0, v13
	v_max_f32_e32 v13, v19, v19
	v_max_f32_e32 v15, v15, v15
	v_lshl_add_u64 v[20:21], v[142:143], 0, s[12:13]
	v_pk_mul_f32 v[16:17], v[16:17], v[16:17]
	v_max_f32_e32 v12, 0, v12
	v_max_f32_e32 v13, 0, v13
	v_max_f32_e32 v15, 0, v15
	s_mov_b32 s12, 0x2c0000
	v_pk_mul_f32 v[18:19], v[12:13], v[12:13]
	v_pk_mul_f32 v[24:25], v[14:15], v[14:15]
	v_cvt_pk_bf16_f32 v12, v16, v17
	v_add_co_u32_e32 v16, vcc, s12, v142
	v_max_f32_e32 v4, v4, v4
	v_max_f32_e32 v5, v5, v5
	v_cvt_pk_bf16_f32 v13, v18, v19
	v_cvt_pk_bf16_f32 v14, v22, v23
	v_cvt_pk_bf16_f32 v15, v24, v25
	v_addc_co_u32_e32 v17, vcc, 0, v143, vcc
	v_max_f32_e32 v4, 0, v4
	v_max_f32_e32 v5, 0, v5
	s_waitcnt lgkmcnt(0)
	global_store_dwordx4 v[36:37], v[226:229], off offset:256
	ds_bpermute_b32 v222, v231, v12
	ds_bpermute_b32 v223, v231, v13
	ds_bpermute_b32 v224, v231, v14
	ds_bpermute_b32 v225, v231, v15
	v_max_f32_e32 v8, v8, v8
	v_max_f32_e32 v9, v9, v9
	v_pk_mul_f32 v[12:13], v[4:5], v[4:5]
	v_max_f32_e32 v5, v6, v6
	v_max_f32_e32 v4, v10, v10
	v_max_f32_e32 v6, 0, v5
	v_max_f32_e32 v5, v11, v11
	v_max_f32_e32 v7, v7, v7
	v_max_f32_e32 v8, 0, v8
	v_max_f32_e32 v9, 0, v9
	v_max_f32_e32 v4, 0, v4
	v_max_f32_e32 v5, 0, v5
	v_max_f32_e32 v7, 0, v7
	v_pk_mul_f32 v[8:9], v[8:9], v[8:9]
	v_pk_mul_f32 v[10:11], v[4:5], v[4:5]
	v_pk_mul_f32 v[14:15], v[6:7], v[6:7]
	v_cvt_pk_bf16_f32 v4, v8, v9
	v_cvt_pk_bf16_f32 v5, v10, v11
	v_cvt_pk_bf16_f32 v6, v12, v13
	v_cvt_pk_bf16_f32 v7, v14, v15
	s_andn2_b64 vcc, exec, s[36:37]
	s_mov_b64 s[36:37], -1
	s_waitcnt lgkmcnt(0)
	global_store_dwordx4 v[16:17], v[222:225], off
	ds_bpermute_b32 v226, v231, v4
	ds_bpermute_b32 v227, v231, v5
	ds_bpermute_b32 v228, v231, v6
	ds_bpermute_b32 v229, v231, v7
	s_waitcnt lgkmcnt(0)
	global_store_dwordx4 v[20:21], v[226:229], off offset:256
	s_cbranch_vccnz .LBB0_690
	s_andn2_b64 vcc, exec, s[0:1]
	s_cbranch_vccnz .LBB0_689
	s_barrier
	s_branch .LBB0_689

.LBB0_766:
	s_lshl_b32 s23, s54, 8
	s_add_i32 s29, s23, 0xffffe000
	s_cmp_eq_u32 s50, 0
	s_cselect_b32 s23, s23, s29
	s_cselect_b32 s29, s31, s27
	s_cselect_b32 s35, s30, s26
	v_lshl_or_b32 v148, s22, 8, v143
	v_add_u32_e32 v150, s23, v1
	v_mov_b32_e32 v146, s35
	v_mov_b32_e32 v147, s29
	v_ashrrev_i32_e32 v149, 31, v148
	v_ashrrev_i32_e32 v151, 31, v150
	v_lshl_add_u64 v[146:147], v[148:149], 1, v[146:147]
	v_lshlrev_b64 v[148:149], 12, v[150:151]
	v_lshl_add_u64 v[148:149], v[146:147], 0, v[148:149]
	s_mov_b32 s23, 0x80000
	s_mov_b64 s[50:51], 0x80000
	v_cvt_pk_bf16_f32 v64, v64, v65
	v_cvt_pk_bf16_f32 v65, v66, v67
	v_cvt_pk_bf16_f32 v66, v60, v61
	v_add_co_u32_e32 v60, vcc, s23, v148
	v_cvt_pk_bf16_f32 v72, v72, v73
	v_cvt_pk_bf16_f32 v73, v74, v75
	v_cvt_pk_bf16_f32 v74, v68, v69
	v_lshl_add_u64 v[68:69], v[148:149], 0, s[50:51]
	v_addc_co_u32_e32 v61, vcc, 0, v149, vcc
	v_cvt_pk_bf16_f32 v48, v48, v49
	v_cvt_pk_bf16_f32 v49, v50, v51
	v_cvt_pk_bf16_f32 v50, v44, v45
	v_cvt_pk_bf16_f32 v51, v46, v47
	s_mov_b32 s23, 0x90000
	ds_bpermute_b32 v222, v231, v48
	ds_bpermute_b32 v223, v231, v49
	ds_bpermute_b32 v224, v231, v50
	ds_bpermute_b32 v225, v231, v51
	s_mov_b64 s[50:51], 0x90000
	v_cvt_pk_bf16_f32 v112, v112, v113
	v_add_co_u32_e32 v50, vcc, s23, v148
	v_cvt_pk_bf16_f32 v113, v114, v115
	v_cvt_pk_bf16_f32 v114, v108, v109
	v_or_b32_e32 v108, 16, v150
	v_lshl_add_u64 v[48:49], v[148:149], 0, s[50:51]
	v_addc_co_u32_e32 v51, vcc, 0, v149, vcc
	v_cvt_pk_bf16_f32 v32, v32, v33
	v_cvt_pk_bf16_f32 v33, v34, v35
	v_cvt_pk_bf16_f32 v34, v28, v29
	v_cvt_pk_bf16_f32 v35, v30, v31
	s_mov_b32 s23, 0xa0000
	v_ashrrev_i32_e32 v109, 31, v108
	v_cvt_pk_bf16_f32 v96, v96, v97
	v_cvt_pk_bf16_f32 v97, v98, v99
	v_cvt_pk_bf16_f32 v98, v92, v93
	v_or_b32_e32 v92, 32, v150
	s_waitcnt lgkmcnt(0)
	global_store_dwordx4 v[68:69], v[222:225], off offset:256
	ds_bpermute_b32 v226, v231, v32
	ds_bpermute_b32 v227, v231, v33
	ds_bpermute_b32 v228, v231, v34
	ds_bpermute_b32 v229, v231, v35
	s_mov_b64 s[50:51], 0xa0000
	v_cvt_pk_bf16_f32 v115, v110, v111
	v_add_co_u32_e32 v34, vcc, s23, v148
	v_lshlrev_b64 v[108:109], 12, v[108:109]
	v_ashrrev_i32_e32 v93, 31, v92
	v_cvt_pk_bf16_f32 v80, v80, v81
	v_cvt_pk_bf16_f32 v81, v82, v83
	v_cvt_pk_bf16_f32 v82, v76, v77
	v_or_b32_e32 v76, 48, v150
	v_lshl_add_u64 v[32:33], v[148:149], 0, s[50:51]
	v_addc_co_u32_e32 v35, vcc, 0, v149, vcc
	v_cvt_pk_bf16_f32 v16, v16, v17
	v_cvt_pk_bf16_f32 v17, v18, v19
	v_cvt_pk_bf16_f32 v18, v12, v13
	v_cvt_pk_bf16_f32 v19, v14, v15
	s_mov_b32 s23, 0xb0000
	s_waitcnt lgkmcnt(0)
	global_store_dwordx4 v[48:49], v[226:229], off offset:256
	ds_bpermute_b32 v222, v231, v112
	ds_bpermute_b32 v223, v231, v113
	ds_bpermute_b32 v224, v231, v114
	ds_bpermute_b32 v225, v231, v115
	v_cvt_pk_bf16_f32 v99, v94, v95
	v_lshlrev_b64 v[92:93], 12, v[92:93]
	v_lshl_add_u64 v[112:113], v[146:147], 0, v[108:109]
	v_ashrrev_i32_e32 v77, 31, v76
	s_waitcnt lgkmcnt(0)
	global_store_dwordx4 v[148:149], v[222:225], off offset:256
	ds_bpermute_b32 v226, v231, v16
	ds_bpermute_b32 v227, v231, v17
	ds_bpermute_b32 v228, v231, v18
	ds_bpermute_b32 v229, v231, v19
	s_waitcnt lgkmcnt(0)
	global_store_dwordx4 v[32:33], v[226:229], off offset:256
	ds_bpermute_b32 v222, v231, v96
	ds_bpermute_b32 v223, v231, v97
	ds_bpermute_b32 v224, v231, v98
	ds_bpermute_b32 v225, v231, v99
	v_cvt_pk_bf16_f32 v83, v78, v79
	v_add_co_u32_e32 v18, vcc, s23, v148
	v_lshl_add_u64 v[96:97], v[146:147], 0, v[92:93]
	v_lshlrev_b64 v[76:77], 12, v[76:77]
	s_mov_b64 s[50:51], 0xb0000
	v_addc_co_u32_e32 v19, vcc, 0, v149, vcc
	v_cvt_pk_bf16_f32 v128, v128, v129
	v_cvt_pk_bf16_f32 v129, v130, v131
	v_cvt_pk_bf16_f32 v130, v124, v125
	v_cvt_pk_bf16_f32 v131, v126, v127
	v_cvt_pk_bf16_f32 v108, v120, v121
	v_cvt_pk_bf16_f32 v109, v122, v123
	v_cvt_pk_bf16_f32 v110, v116, v117
	v_cvt_pk_bf16_f32 v111, v118, v119
	v_cvt_pk_bf16_f32 v92, v104, v105
	v_cvt_pk_bf16_f32 v93, v106, v107
	v_cvt_pk_bf16_f32 v94, v100, v101
	v_cvt_pk_bf16_f32 v95, v102, v103
	s_waitcnt lgkmcnt(0)
	global_store_dwordx4 v[112:113], v[222:225], off offset:256
	ds_bpermute_b32 v226, v231, v80
	ds_bpermute_b32 v227, v231, v81
	ds_bpermute_b32 v228, v231, v82
	ds_bpermute_b32 v229, v231, v83
	v_cvt_pk_bf16_f32 v78, v84, v85
	v_cvt_pk_bf16_f32 v79, v86, v87
	v_lshl_add_u64 v[80:81], v[146:147], 0, v[76:77]
	v_cvt_pk_bf16_f32 v76, v88, v89
	v_cvt_pk_bf16_f32 v77, v90, v91
	v_cvt_pk_bf16_f32 v75, v70, v71
	v_cvt_pk_bf16_f32 v67, v62, v63
	v_cvt_pk_bf16_f32 v44, v56, v57
	v_cvt_pk_bf16_f32 v45, v58, v59
	v_cvt_pk_bf16_f32 v46, v52, v53
	v_cvt_pk_bf16_f32 v47, v54, v55
	v_cvt_pk_bf16_f32 v28, v40, v41
	v_cvt_pk_bf16_f32 v29, v42, v43
	v_cvt_pk_bf16_f32 v30, v36, v37
	v_cvt_pk_bf16_f32 v31, v38, v39
	v_lshl_add_u64 v[16:17], v[148:149], 0, s[50:51]
	v_cvt_pk_bf16_f32 v12, v24, v25
	v_cvt_pk_bf16_f32 v13, v26, v27
	v_cvt_pk_bf16_f32 v14, v20, v21
	v_cvt_pk_bf16_f32 v15, v22, v23
	v_cvt_pk_bf16_f32 v8, v8, v9
	v_cvt_pk_bf16_f32 v9, v10, v11
	v_cvt_pk_bf16_f32 v10, v4, v5
	v_cvt_pk_bf16_f32 v11, v6, v7
	s_and_b64 vcc, exec, s[0:1]
	s_mov_b64 s[0:1], -1
	s_waitcnt lgkmcnt(0)
	global_store_dwordx4 v[96:97], v[226:229], off offset:256
	ds_bpermute_b32 v222, v231, v128
	ds_bpermute_b32 v223, v231, v129
	ds_bpermute_b32 v224, v231, v130
	ds_bpermute_b32 v225, v231, v131
	s_waitcnt lgkmcnt(0)
	global_store_dwordx4 v[148:149], v[222:225], off
	ds_bpermute_b32 v226, v231, v108
	ds_bpermute_b32 v227, v231, v109
	ds_bpermute_b32 v228, v231, v110
	ds_bpermute_b32 v229, v231, v111
	s_waitcnt lgkmcnt(0)
	global_store_dwordx4 v[112:113], v[226:229], off
	ds_bpermute_b32 v222, v231, v92
	ds_bpermute_b32 v223, v231, v93
	ds_bpermute_b32 v224, v231, v94
	ds_bpermute_b32 v225, v231, v95
	s_waitcnt lgkmcnt(0)
	global_store_dwordx4 v[96:97], v[222:225], off
	ds_bpermute_b32 v226, v231, v76
	ds_bpermute_b32 v227, v231, v77
	ds_bpermute_b32 v228, v231, v78
	ds_bpermute_b32 v229, v231, v79
	s_waitcnt lgkmcnt(0)
	global_store_dwordx4 v[80:81], v[226:229], off
	ds_bpermute_b32 v222, v231, v72
	ds_bpermute_b32 v223, v231, v73
	ds_bpermute_b32 v224, v231, v74
	ds_bpermute_b32 v225, v231, v75
	s_waitcnt lgkmcnt(0)
	global_store_dwordx4 v[80:81], v[222:225], off offset:256
	ds_bpermute_b32 v226, v231, v64
	ds_bpermute_b32 v227, v231, v65
	ds_bpermute_b32 v228, v231, v66
	ds_bpermute_b32 v229, v231, v67
	s_waitcnt lgkmcnt(0)
	global_store_dwordx4 v[60:61], v[226:229], off
	ds_bpermute_b32 v222, v231, v44
	ds_bpermute_b32 v223, v231, v45
	ds_bpermute_b32 v224, v231, v46
	ds_bpermute_b32 v225, v231, v47
	s_waitcnt lgkmcnt(0)
	global_store_dwordx4 v[50:51], v[222:225], off
	ds_bpermute_b32 v226, v231, v28
	ds_bpermute_b32 v227, v231, v29
	ds_bpermute_b32 v228, v231, v30
	ds_bpermute_b32 v229, v231, v31
	s_waitcnt lgkmcnt(0)
	global_store_dwordx4 v[34:35], v[226:229], off
	ds_bpermute_b32 v222, v231, v12
	ds_bpermute_b32 v223, v231, v13
	ds_bpermute_b32 v224, v231, v14
	ds_bpermute_b32 v225, v231, v15
	s_waitcnt lgkmcnt(0)
	global_store_dwordx4 v[18:19], v[222:225], off
	ds_bpermute_b32 v226, v231, v8
	ds_bpermute_b32 v227, v231, v9
	ds_bpermute_b32 v228, v231, v10
	ds_bpermute_b32 v229, v231, v11
	s_waitcnt lgkmcnt(0)
	global_store_dwordx4 v[16:17], v[226:229], off offset:256
	s_cbranch_vccnz .LBB0_757
	s_andn2_b64 vcc, exec, s[36:37]
	s_cbranch_vccnz .LBB0_756
	s_barrier
	s_branch .LBB0_756
